# P9->P10 panel barrier split: arrival at the seam, the wait (wave 0) moved behind the first unit's prologue requests of P10, which do not depend on the panel
# speedup vs baseline: 1.0077x; 1.0032x over previous
; __device__ __forceinline__ unsigned xb_add(unsigned* p, unsigned v) { return __hip_atomic_fetch_add(p, v, __ATOMIC_RELAXED, __HIP_MEMORY_SCOPE_AGENT); }
; #define SEAM(k) do { if (IN(k) && IN((k) + 1)) xcd_barrier(bar); } while (0)
; #define PH(k) if (IN(k)) for (int rep_ = 0; rep_ <= ((PROBE_REPEAT >> (k)) & 1); ++rep_)
; #define REPBAR() do { if (rep_) xcd_barrier(bar); } while (0)
; __device__ __forceinline__ void xcd_barrier(const XcdBarrier& b) {
;     asm volatile("s_waitcnt vmcnt(0)" ::: "memory");
;     __syncthreads();
;     if (threadIdx.x == 0) {
;         unsigned* bar = b.bar;
;         __builtin_amdgcn_s_waitcnt(0);
;         unsigned nloc = b.st[0], nx = b.st[1];
;         if (nloc == 0u) { xcd_barrier_complete(bar, b.x, nloc, nx); b.st[0] = nloc; b.st[1] = nx; }
;         const unsigned old = xb_add(&bar[XB_XSUB(b.x)], 1u);
; __global__ void __launch_bounds__(512, 2) mega(MegaArgs a) {
;     ...
;     SEAM(9);
;     PH(10) { REPBAR();
.LBB0_822:
	s_cmp_gt_i32 s87, 10
	s_cselect_b64 s[2:3], -1, 0
	s_and_b64 s[0:1], s[0:1], s[2:3]
	s_andn2_b64 vcc, exec, s[0:1]
	s_cbranch_vccnz .LBB0_876
	s_waitcnt vmcnt(0)
	s_waitcnt vmcnt(0) lgkmcnt(0)
	s_barrier
	s_and_saveexec_b64 s[0:1], s[88:89]
	s_cbranch_execz .LBB0_875
	v_readlane_b32 s4, v250, 6
	v_readlane_b32 s5, v250, 7
	v_readlane_b32 s6, v250, 28
	v_mov_b32_e32 v2, 0
	v_mov_b32_e32 v3, 1
	s_lshr_b32 s6, s6, 3
	s_and_b32 s7, s6, 7
	s_bfe_u32 s6, s6, 0x30003
	s_lshl_b32 s7, s7, 3
	s_add_i32 s6, s6, s7
	s_lshl_b32 s8, s6, 1
	s_and_b32 s8, s8, 63
	s_lshl_b32 s6, s6, 8
	s_lshl_b32 s8, s8, 8
	s_add_u32 s4, s4, 0x4c040
	s_addc_u32 s5, s5, 0
	s_add_u32 s8, s4, s8
	s_addc_u32 s9, s5, 0
	s_add_u32 s4, s4, s6
	s_addc_u32 s5, s5, 0
	s_mov_b32 s7, 0
	s_mov_b64 s[100:101], s[4:5]
	global_atomic_add v2, v3, s[4:5]

;     __host__ __device__ bool next(int i, Unit& u) const { if (i > 1) return false; Unit b; if (!S.next(0, b)) return false; u.pm = b.pm + i * nM; u.pn = b.pn + i * nN; return true; }
; #define PG8_STAGE(bufoff, gbase, voff) do { _Pragma("unroll") for (int _i = 0; _i < 2; ++_i) \
;         __builtin_amdgcn_global_load_lds((const unsigned*)((const char*)(gbase) + (voff)[_i]), (PG8_LAS unsigned*)(lds + (bufoff) + ldsw + _i * 8192), 16, 0, 0); } while (0)
; template <class Epi, class Sched, bool ALIGN_EPI = false, bool SP2 = false>
; __device__ __forceinline__ void gemm_phase(PG8_LAS unsigned char* lds, const Gemm g, const Sched& S, const Epi& E) {
;     ...
;     const int tid = tid_l, wid = __builtin_amdgcn_readfirstlane(tid >> 6), lane = tid & 63, wr = wid >> 2, wc = wid & 3, fr = lane & 15, fq = lane >> 4;
;     const int K = g.K, nt = K / BK;
;     unsigned voffA[2], voffB[2];
; #pragma unroll
;     for (int i = 0; i < 2; ++i) { int R, C; stage_rc(tid * 16 + i * 8192, R, C); const int Rb = Epi::PERM ? ((R & ~31) + perm32(R & 31)) : R;
;         voffA[i] = (unsigned)(R * K + C) * 2u; voffB[i] = (unsigned)(Rb * K + C) * 2u; }
;     const size_t kstep = (size_t)(BK * 2);
;     const size_t hstep = (size_t)HALF * K * 2;
;     const size_t tstep = 2 * hstep;
;     const unsigned ldsw = (unsigned)wid * 1024u;
;     const int aoff = lds_byte(wr * 64 + fr, fq * 8), boff = lds_byte(wc * 32 + fr, fq * 8);
;     ...
;     Unit cur, nxt; int ui = 0;
;     if (!S.next(0, cur)) return;
;     f32x4 acc[2][2][4][2];
; #pragma unroll
;     for (int a = 0; a < 2; ++a)
; #pragma unroll
;         for (int b = 0; b < 2; ++b)
; #pragma unroll
;             for (int m = 0; m < 4; ++m)
; #pragma unroll
;                 for (int n = 0; n < 2; ++n) acc[a][b][m][n] = (f32x4){0.f, 0.f, 0.f, 0.f};
;     bf16x8 At[4][2], B0[2][2], B1[2][2];
;     const char* cA = g.atile(cur.pm, tstep); const char* cB = (const char*)g.Bt + (size_t)cur.pn * tstep;
;     S.a_ready(cur);
;     if constexpr (SP2) {
;         PG8_STAGE(PG8_SB(0, 0), cB, voffB); PG8_STAGE(PG8_SB(0, 1), cB + hstep, voffB); PG8_STAGE(PG8_SA(0, 0), cA, voffA); PG8_STAGE(PG8_SA(0, 1), cA + hstep, voffA);
.LBB0_876:
	s_cmp_lt_i32 s86, 11
	s_cselect_b64 s[0:1], -1, 0
	s_and_b64 s[0:1], s[0:1], s[2:3]
	s_andn2_b64 vcc, exec, s[0:1]
	v_cmp_ne_u32_e64 s[36:37], 1, v164
	s_cbranch_vccnz .LBB0_895
	s_nop 0
	v_mov_b32_e32 v16, v0
	s_and_b64 vcc, exec, s[36:37]
	s_waitcnt lgkmcnt(0)
	v_readfirstlane_b32 s14, v16
	s_cbranch_vccnz .LBB0_895
	v_lshlrev_b32_e32 v2, 4, v16
	v_add_u32_e32 v3, 0x2000, v2
	v_ashrrev_i32_e32 v4, 31, v3
	v_lshrrev_b32_e32 v4, 22, v4
	v_add_u32_e32 v4, v3, v4
	v_ashrrev_i32_e32 v10, 10, v4
	v_mul_i32_i24_e32 v4, 0x400, v10
	v_sub_u32_e32 v3, v3, v4
	v_lshrrev_b32_e32 v4, 4, v3
	v_bitop3_b32 v3, v4, v3, 32 bitop3:0x6c
	v_ashrrev_i32_e32 v4, 31, v3
	v_lshrrev_b32_e32 v4, 26, v4
	v_add_u32_e32 v4, v3, v4
	v_lshlrev_b32_e32 v5, 3, v10
	v_ashrrev_i32_e32 v11, 6, v4
	v_and_b32_e32 v5, -16, v5
	v_readlane_b32 s2, v252, 9
	v_add_u32_e32 v5, v11, v5
	s_mul_i32 s4, s2, 33
	s_lshl_b32 s5, s2, 5
	v_and_b32_e32 v6, 3, v11
	s_mov_b32 s2, 0x1fffe0
	v_lshrrev_b32_e32 v7, 2, v5
	v_lshlrev_b32_e32 v8, 1, v5
	v_and_b32_e32 v4, 0xc0, v4
	v_and_or_b32 v6, v5, s2, v6
	v_and_b32_e32 v7, 4, v7
	v_and_b32_e32 v8, 24, v8
	v_sub_u32_e32 v3, v3, v4
	v_mov_b32_e32 v4, 1
	v_or3_b32 v6, v6, v7, v8
	v_lshlrev_b32_e32 v7, 5, v10
	v_ashrrev_i16_sdwa v3, v4, sext(v3) dst_sel:DWORD dst_unused:UNUSED_PAD src0_sel:DWORD src1_sel:BYTE_0
	v_and_b32_e32 v7, 32, v7
	v_bfe_i32 v12, v3, 0, 16
	v_add_lshl_u32 v3, v7, v12, 1
	v_lshl_add_u32 v134, v6, 11, v3
	v_lshl_add_u32 v136, v5, 11, v3
	v_bfe_i32 v3, v16, 27, 1
	v_lshrrev_b32_e32 v3, 22, v3
	v_add_u32_e32 v3, v2, v3
	v_and_b32_e32 v3, 0xfffffc00, v3
	v_sub_u32_e32 v2, v2, v3
	v_lshrrev_b32_e32 v3, 4, v2
	v_ashrrev_i32_e32 v5, 31, v16
	v_bitop3_b32 v2, v3, v2, 32 bitop3:0x6c
	v_lshrrev_b32_e32 v5, 26, v5
	v_ashrrev_i32_e32 v3, 31, v2
	v_add_u32_e32 v5, v16, v5
	v_lshrrev_b32_e32 v3, 26, v3
	v_ashrrev_i32_e32 v14, 6, v5
	v_add_u32_e32 v3, v2, v3
	v_lshlrev_b32_e32 v5, 3, v14
	v_ashrrev_i32_e32 v13, 6, v3
	v_and_b32_e32 v5, -16, v5
	v_add_u32_e32 v5, v13, v5
	v_and_b32_e32 v6, 3, v13
	s_ashr_i32 s12, s14, 6
	v_and_or_b32 v6, v5, s2, v6
	v_readlane_b32 s2, v252, 7
	s_ashr_i32 s13, s14, 8
	s_lshl_b32 s33, s12, 10
	v_readlane_b32 s3, v252, 8
	s_and_b64 s[2:3], s[2:3], exec
	s_cselect_b32 s2, s4, s5
	v_readlane_b32 s3, v252, 10
	s_add_i32 s2, s2, s3
	s_ashr_i32 s3, s2, 31
	s_lshr_b32 s3, s3, 27
	s_add_i32 s3, s2, s3
	s_ashr_i32 s4, s3, 5
	s_andn2_b32 s3, s3, 31
	s_sub_i32 s16, s2, s3
	s_bfe_i32 s2, s16, 0x80000
	s_bfe_u32 s2, s2, 0x3000c
	s_add_i32 s2, s16, s2
	s_bfe_i32 s3, s2, 0x80000
	s_and_b32 s2, s2, 0xf8
	s_sub_i32 s2, s16, s2
	s_lshl_b32 s17, s4, 3
	s_sext_i32_i16 s3, s3
	s_sext_i32_i8 s2, s2
	v_lshrrev_b32_e32 v7, 2, v5
	v_lshlrev_b32_e32 v8, 1, v5
	v_and_b32_e32 v3, 0xc0, v3
	s_lshr_b32 s6, s3, 3
	s_add_i32 s42, s17, s2
	v_and_b32_e32 v7, 4, v7
	v_and_b32_e32 v8, 24, v8
	v_sub_u32_e32 v2, v2, v3
	s_ashr_i32 s43, s42, 31
	s_bfe_i64 s[4:5], s[6:7], 0x100000
	v_or3_b32 v6, v6, v7, v8
	v_lshlrev_b32_e32 v7, 5, v14
	v_ashrrev_i16_sdwa v2, v4, sext(v2) dst_sel:DWORD dst_unused:UNUSED_PAD src0_sel:DWORD src1_sel:BYTE_0
	s_lshl_b64 s[2:3], s[42:43], 19
	s_lshl_b64 s[4:5], s[4:5], 19
	v_and_b32_e32 v7, 32, v7
	v_bfe_i32 v15, v2, 0, 16
	s_add_u32 s46, s64, s4
	v_add_lshl_u32 v2, v7, v15, 1
	s_addc_u32 s47, s65, s5
	s_add_i32 s50, s33, 0
	v_lshl_add_u32 v138, v6, 11, v2
	s_add_i32 m0, s50, 0x10000
	v_readlane_b32 s20, v250, 0
	global_load_lds_dwordx4 v138, s[46:47]
	s_add_i32 m0, s50, 0x12000
	s_add_u32 s4, s46, 0x40000
	global_load_lds_dwordx4 v134, s[46:47]
	s_addc_u32 s5, s47, 0
	s_add_i32 m0, s50, 0x14000
	v_readlane_b32 s21, v250, 1
	v_readlane_b32 s22, v250, 2
	v_readlane_b32 s23, v250, 3
	v_readlane_b32 s24, v250, 4
	v_readlane_b32 s25, v250, 5
	global_load_lds_dwordx4 v138, s[4:5]
	s_add_i32 m0, s50, 0x16000
	v_readlane_b32 s26, v250, 6
	v_readlane_b32 s27, v250, 7
	s_mov_b64 s[20:21], s[24:25]
	s_add_u32 s44, s20, s2
	s_addc_u32 s45, s21, s3
	s_add_i32 s51, s50, 0x2000
	v_lshl_add_u32 v140, v5, 11, v2
	global_load_lds_dwordx4 v134, s[4:5]
	s_mov_b32 m0, s50
	s_add_u32 s2, s44, 0x40000
	global_load_lds_dwordx4 v140, s[44:45]
	s_mov_b32 m0, s51
	s_addc_u32 s3, s45, 0
	s_add_i32 s52, s50, 0x4000
	global_load_lds_dwordx4 v136, s[44:45]
	s_mov_b32 m0, s52
	s_add_i32 s53, s50, 0x6000
	global_load_lds_dwordx4 v140, s[2:3]
	s_mov_b32 m0, s53
	v_mov_b32_e32 v139, 0
	global_load_lds_dwordx4 v136, s[2:3]
	s_cmp_lg_u64 s[88:89], 0
	s_cbranch_scc0 .Lpb9_skip
	v_mov_b32_e32 v2, 0
	s_mov_b32 s98, 0
.Lpb9_poll:
	global_load_dword v3, v2, s[100:101] sc1
	s_add_i32 s98, s98, 1
	s_waitcnt vmcnt(0)
	s_nop 0
	v_readfirstlane_b32 s99, v3
	s_nop 0
	s_nop 0
	s_cmp_ge_u32 s99, 4
	s_cbranch_scc1 .Lpb9_done
	s_cmp_ge_u32 s98, 0x400000
	s_cbranch_scc1 .Lpb9_done
	s_sleep 1
	s_branch .Lpb9_poll

; #define PG8_STAGE(bufoff, gbase, voff) do { _Pragma("unroll") for (int _i = 0; _i < 2; ++_i) \
;         __builtin_amdgcn_global_load_lds((const unsigned*)((const char*)(gbase) + (voff)[_i]), (PG8_LAS unsigned*)(lds + (bufoff) + ldsw + _i * 8192), 16, 0, 0); } while (0)
; #define PG8_WAIT_V(n) asm volatile("s_waitcnt vmcnt(" #n ")" ::: "memory")
; #define PG8_BAR __builtin_amdgcn_s_barrier()
; template <class Epi, class Sched, bool ALIGN_EPI = false, bool SP2 = false>
; __device__ __forceinline__ void gemm_phase(PG8_LAS unsigned char* lds, const Gemm g, const Sched& S, const Epi& E) {
;     ...
;         PG8_STAGE(PG8_SB(0, 0), cB, voffB); PG8_STAGE(PG8_SB(0, 1), cB + hstep, voffB); PG8_STAGE(PG8_SA(0, 0), cA, voffA); PG8_STAGE(PG8_SA(0, 1), cA + hstep, voffA);
;         if (wr == 1) PG8_BAR;
;         PG8_WAIT_V(2); PG8_BAR;
.Lpb9_skip:
	s_nop 0
	v_mov_b32_e32 v135, v139
	v_mov_b32_e32 v141, v139
	v_mov_b32_e32 v137, v139
	s_cmp_eq_u32 s13, 1
	v_lshl_add_u64 v[8:9], s[46:47], 0, v[138:139]
	v_lshl_add_u64 v[4:5], s[46:47], 0, v[134:135]
	s_mov_b64 s[2:3], 0x40000
	v_lshl_add_u64 v[2:3], s[44:45], 0, v[140:141]
	s_cselect_b64 s[4:5], -1, 0
	s_cmp_lg_u32 s13, 1
	v_lshl_add_u64 v[6:7], s[44:45], 0, v[136:137]
	s_mov_b64 s[22:23], s[26:27]
	s_cbranch_scc1 .LBB0_880
	s_barrier
